# out-GEMM epilogue: residual loads of both column halves of a row group issued together (second half into spare registers) - 8 instead of 16 exposed round trips per tile
# baseline (speedup 1.0000x reference)
.LBB0_1012:
	s_ashr_i32 s17, s24, 4
	s_mul_hi_i32 s19, s17, 0x6000
	s_mulk_i32 s17, 0x6000
	s_add_u32 s17, s96, s17
	s_addc_u32 s19, s97, s19
	v_lshl_or_b32 v162, s26, 8, v181
	s_add_u32 s26, s17, 0x2000
	s_addc_u32 s27, s19, 0
	s_add_u32 s28, s17, 0x4000
	s_addc_u32 s29, s19, 0
	v_ashrrev_i32_e32 v163, 31, v162
	s_lshl_b32 s17, s24, 8
	v_lshlrev_b64 v[80:81], 2, v[162:163]
	v_add_u32_e32 v166, s17, v176
	v_lshl_add_u64 v[92:93], s[76:77], 0, v[80:81]
	v_lshl_add_u64 v[84:85], s[28:29], 0, v[80:81]
	v_ashrrev_i32_e32 v167, 31, v166
	global_load_dwordx4 v[188:191], v[92:93], off offset:16
	global_load_dwordx4 v[168:171], v[92:93], off
	global_load_dwordx4 v[172:175], v[84:85], off offset:16
	global_load_dwordx4 v[192:195], v[84:85], off
	v_lshlrev_b64 v[84:85], 12, v[166:167]
	v_lshl_add_u64 v[84:85], s[64:65], 0, v[84:85]
	v_lshl_add_u64 v[220:221], v[84:85], 0, v[80:81]
	v_lshl_add_u64 v[82:83], s[26:27], 0, v[80:81]
	global_load_dwordx4 v[196:199], v[220:221], off
	global_load_dwordx4 v[88:91], v[82:83], off
	global_load_dwordx4 v[84:87], v[82:83], off offset:16
	global_load_dwordx4 v[200:203], v[220:221], off offset:16
	global_load_dwordx4 v[232:235], v[220:221], off offset:512
	global_load_dwordx4 v[236:239], v[220:221], off offset:528
	v_or_b32_e32 v80, 0x80, v162
	v_or_b32_e32 v82, 0x84, v162
	v_ashrrev_i32_e32 v81, 31, v80
	v_lshlrev_b64 v[222:223], 11, v[166:167]
	v_ashrrev_i32_e32 v83, 31, v82
	v_lshlrev_b64 v[164:165], 1, v[162:163]
	v_lshlrev_b64 v[80:81], 2, v[80:81]
	v_lshl_add_u64 v[224:225], s[52:53], 0, v[222:223]
	global_load_dwordx4 v[204:207], v[92:93], off offset:528
	global_load_dwordx4 v[208:211], v[92:93], off offset:512
	v_lshl_add_u64 v[92:93], s[26:27], 0, v[80:81]
	v_lshl_add_u64 v[82:83], v[82:83], 2, s[26:27]
	v_lshl_add_u64 v[80:81], s[28:29], 0, v[80:81]
	v_lshl_add_u64 v[222:223], s[12:13], 0, v[222:223]
	v_lshl_add_u64 v[224:225], v[224:225], 0, v[164:165]
	global_load_dwordx4 v[92:95], v[92:93], off
	s_nop 0
	global_load_dwordx4 v[212:215], v[80:81], off
	global_load_dwordx4 v[216:219], v[80:81], off offset:16
	s_nop 0
	global_load_dwordx4 v[80:83], v[82:83], off
	v_lshl_add_u64 v[222:223], v[222:223], 0, v[164:165]
	s_waitcnt vmcnt(0)
	v_pk_add_f32 v[226:227], v[174:175], 1.0 op_sel_hi:[1,0]
	v_pk_add_f32 v[194:195], v[194:195], 1.0 op_sel_hi:[1,0]
	v_pk_add_f32 v[192:193], v[192:193], 1.0 op_sel_hi:[1,0]
	v_pk_add_f32 v[172:173], v[172:173], 1.0 op_sel_hi:[1,0]
	v_pk_mul_f32 v[170:171], v[170:171], v[194:195]
	v_pk_mul_f32 v[174:175], v[168:169], v[192:193]
	v_pk_mul_f32 v[168:169], v[190:191], v[226:227]
	v_pk_mul_f32 v[172:173], v[188:189], v[172:173]
	v_pk_fma_f32 v[198:199], v[142:143], v[90:91], v[198:199]
	v_pk_fma_f32 v[226:227], v[140:141], v[88:89], v[196:197]
	v_pk_fma_f32 v[202:203], v[138:139], v[86:87], v[202:203]
	v_pk_fma_f32 v[200:201], v[136:137], v[84:85], v[200:201]
	v_cvt_pk_bf16_f32 v136, v226, v227
	v_cvt_pk_bf16_f32 v137, v198, v199
	v_cvt_pk_bf16_f32 v138, v200, v201
	v_cvt_pk_bf16_f32 v139, v202, v203
	v_pk_mul_f32 v[140:141], v[170:171], v[198:199]
	v_pk_mul_f32 v[142:143], v[174:175], v[226:227]
	v_pk_mul_f32 v[188:189], v[168:169], v[202:203]
	v_pk_mul_f32 v[190:191], v[172:173], v[200:201]
	global_store_dwordx4 v[224:225], v[136:139], off
	v_mul_f32_e32 v199, v199, v199
	v_mul_f32_e32 v201, v201, v201
	v_cvt_pk_bf16_f32 v136, v142, v143
	v_cvt_pk_bf16_f32 v137, v140, v141
	v_cvt_pk_bf16_f32 v138, v190, v191
	v_cvt_pk_bf16_f32 v139, v188, v189
	global_store_dwordx4 v[222:223], v[136:139], off
	s_waitcnt vmcnt(8)
	s_nop 1
	v_mov_b32_e32 v190, v232
	v_mov_b32_e32 v191, v233
	v_mov_b32_e32 v192, v234
	v_mov_b32_e32 v193, v235
	v_mov_b32_e32 v194, v236
	v_mov_b32_e32 v195, v237
	v_mov_b32_e32 v196, v238
	v_mov_b32_e32 v197, v239
	v_mul_f32_e32 v189, v227, v227
	v_and_b32_e32 v137, 64, v186
	v_fmac_f32_e32 v189, v226, v226
	v_fmac_f32_e32 v199, v198, v198
	v_xor_b32_e32 v136, 16, v186
	v_add_u32_e32 v137, 64, v137
	v_mul_f32_e32 v203, v203, v203
	v_fmac_f32_e32 v201, v200, v200
	v_add_f32_e32 v189, v189, v199
	v_cmp_lt_i32_e32 vcc, v136, v137
	v_fmac_f32_e32 v203, v202, v202
	v_add_f32_e32 v189, v189, v201
	v_cndmask_b32_e32 v136, v186, v136, vcc
	v_add_f32_e32 v189, v203, v189
	v_lshlrev_b32_e32 v188, 2, v136
	v_xor_b32_e32 v138, 32, v186
	v_cmp_lt_i32_e32 vcc, v138, v137
	v_pk_fma_f32 v[134:135], v[134:135], v[94:95], v[192:193]
	v_pk_fma_f32 v[132:133], v[132:133], v[92:93], v[190:191]
	v_pk_fma_f32 v[190:191], v[130:131], v[82:83], v[196:197]
	v_pk_fma_f32 v[192:193], v[128:129], v[80:81], v[194:195]
	v_mul_f32_e32 v194, v133, v133
	v_mul_f32_e32 v195, v135, v135
	v_cvt_pk_bf16_f32 v128, v132, v133
	v_cvt_pk_bf16_f32 v129, v134, v135
	v_cvt_pk_bf16_f32 v130, v192, v193
	v_cvt_pk_bf16_f32 v131, v190, v191
	v_mul_f32_e32 v196, v193, v193
	v_fmac_f32_e32 v194, v132, v132
	v_fmac_f32_e32 v195, v134, v134
	v_mul_f32_e32 v197, v191, v191
	global_store_dwordx4 v[224:225], v[128:131], off offset:256
	v_fmac_f32_e32 v196, v192, v192
	v_fmac_f32_e32 v197, v190, v190
	v_add_f32_e32 v128, v194, v195
	v_add_f32_e32 v128, v128, v196
	v_add_f32_e32 v128, v197, v128
	v_add_f32_e32 v131, v189, v128
	v_mov_b32_e32 v189, v131
	s_nop 1
	v_permlane16_swap_b32_e32 v189, v131
	v_cndmask_b32_e32 v137, v186, v138, vcc
	v_pk_add_f32 v[138:139], v[212:213], 1.0 op_sel_hi:[1,0]
	v_lshlrev_b32_e32 v187, 2, v137
	v_pk_mul_f32 v[140:141], v[208:209], v[138:139]
	v_pk_add_f32 v[136:137], v[214:215], 1.0 op_sel_hi:[1,0]
	v_pk_mul_f32 v[128:129], v[140:141], v[132:133]
	v_pk_add_f32 v[212:213], v[218:219], 1.0 op_sel_hi:[1,0]
	v_cvt_pk_bf16_f32 v130, v128, v129
	s_waitcnt lgkmcnt(0)
	v_add_f32_e32 v128, v131, v189
	v_mov_b32_e32 v129, v128
	s_nop 1
	v_permlane32_swap_b32_e32 v129, v128
	v_pk_add_f32 v[214:215], v[216:217], 1.0 op_sel_hi:[1,0]
	v_pk_mul_f32 v[142:143], v[210:211], v[136:137]
	v_pk_mul_f32 v[136:137], v[206:207], v[212:213]
	v_pk_mul_f32 v[138:139], v[204:205], v[214:215]
	v_pk_mul_f32 v[134:135], v[142:143], v[134:135]
	v_pk_mul_f32 v[190:191], v[136:137], v[190:191]
	v_pk_mul_f32 v[132:133], v[138:139], v[192:193]
	v_cvt_pk_bf16_f32 v131, v134, v135
	v_cvt_pk_bf16_f32 v132, v132, v133
	v_cvt_pk_bf16_f32 v133, v190, v191
	global_store_dwordx4 v[222:223], v[130:133], off offset:256
	s_and_saveexec_b64 s[24:25], s[2:3]
	s_cbranch_execz .LBB0_1014
	v_lshl_add_u64 v[130:131], v[166:167], 2, s[14:15]
	s_waitcnt lgkmcnt(0)
	v_add_f32_e32 v128, v128, v129
	global_atomic_add_f32 v[130:131], v128, off
.LBB0_1014:
	s_or_b64 exec, exec, s[24:25]
	v_add_u32_e32 v128, s17, v178
	s_waitcnt lgkmcnt(0)
	v_ashrrev_i32_e32 v129, 31, v128
	v_lshlrev_b64 v[130:131], 12, v[128:129]
	v_lshl_add_u64 v[130:131], s[64:65], 0, v[130:131]
	v_lshl_add_u64 v[134:135], v[162:163], 2, v[130:131]
	global_load_dwordx4 v[130:133], v[134:135], off
	global_load_dwordx4 v[190:193], v[134:135], off offset:16
	global_load_dwordx4 v[232:235], v[134:135], off offset:512
	global_load_dwordx4 v[236:239], v[134:135], off offset:528
	v_lshlrev_b64 v[194:195], 11, v[128:129]
	v_lshl_add_u64 v[196:197], s[52:53], 0, v[194:195]
	v_lshl_add_u64 v[194:195], s[12:13], 0, v[194:195]
	v_lshl_add_u64 v[196:197], v[196:197], 0, v[164:165]
	v_lshl_add_u64 v[194:195], v[194:195], 0, v[164:165]
	s_waitcnt vmcnt(3)
	v_pk_fma_f32 v[132:133], v[126:127], v[90:91], v[132:133]
	v_pk_fma_f32 v[130:131], v[124:125], v[88:89], v[130:131]
	s_waitcnt vmcnt(2)
	v_pk_fma_f32 v[192:193], v[122:123], v[86:87], v[192:193]
	v_pk_fma_f32 v[190:191], v[120:121], v[84:85], v[190:191]
	v_cvt_pk_bf16_f32 v120, v130, v131
	v_cvt_pk_bf16_f32 v121, v132, v133
	v_cvt_pk_bf16_f32 v122, v190, v191
	v_cvt_pk_bf16_f32 v123, v192, v193
	v_pk_mul_f32 v[124:125], v[170:171], v[132:133]
	v_pk_mul_f32 v[126:127], v[174:175], v[130:131]
	v_pk_mul_f32 v[198:199], v[168:169], v[192:193]
	v_pk_mul_f32 v[200:201], v[172:173], v[190:191]
	global_store_dwordx4 v[196:197], v[120:123], off
	v_mul_f32_e32 v131, v131, v131
	v_mul_f32_e32 v133, v133, v133
	v_cvt_pk_bf16_f32 v120, v126, v127
	v_cvt_pk_bf16_f32 v121, v124, v125
	v_cvt_pk_bf16_f32 v122, v200, v201
	v_cvt_pk_bf16_f32 v123, v198, v199
	global_store_dwordx4 v[194:195], v[120:123], off
	s_waitcnt vmcnt(2)
	s_nop 1
	v_mov_b32_e32 v120, v232
	v_mov_b32_e32 v121, v233
	v_mov_b32_e32 v122, v234
	v_mov_b32_e32 v123, v235
	v_mov_b32_e32 v124, v236
	v_mov_b32_e32 v125, v237
	v_mov_b32_e32 v126, v238
	v_mov_b32_e32 v127, v239
	v_mul_f32_e32 v134, v191, v191
	v_fmac_f32_e32 v131, v130, v130
	v_fmac_f32_e32 v133, v132, v132
	v_mul_f32_e32 v135, v193, v193
	v_fmac_f32_e32 v134, v190, v190
	v_add_f32_e32 v130, v131, v133
	v_fmac_f32_e32 v135, v192, v192
	v_add_f32_e32 v130, v130, v134
	v_add_f32_e32 v130, v135, v130
	v_pk_fma_f32 v[118:119], v[118:119], v[94:95], v[122:123]
	v_pk_fma_f32 v[116:117], v[116:117], v[92:93], v[120:121]
	v_pk_fma_f32 v[120:121], v[114:115], v[82:83], v[126:127]
	v_pk_fma_f32 v[122:123], v[112:113], v[80:81], v[124:125]
	v_mul_f32_e32 v124, v117, v117
	v_mul_f32_e32 v125, v119, v119
	v_cvt_pk_bf16_f32 v112, v116, v117
	v_cvt_pk_bf16_f32 v113, v118, v119
	v_cvt_pk_bf16_f32 v114, v122, v123
	v_cvt_pk_bf16_f32 v115, v120, v121
	v_mul_f32_e32 v126, v123, v123
	v_fmac_f32_e32 v124, v116, v116
	v_fmac_f32_e32 v125, v118, v118
	v_mul_f32_e32 v127, v121, v121
	global_store_dwordx4 v[196:197], v[112:115], off offset:256
	v_fmac_f32_e32 v126, v122, v122
	v_fmac_f32_e32 v127, v120, v120
	v_add_f32_e32 v112, v124, v125
	v_add_f32_e32 v112, v112, v126
	v_add_f32_e32 v112, v127, v112
	v_add_f32_e32 v115, v130, v112
	v_mov_b32_e32 v124, v115
	s_nop 1
	v_permlane16_swap_b32_e32 v124, v115
	v_pk_mul_f32 v[112:113], v[140:141], v[116:117]
	v_pk_mul_f32 v[118:119], v[142:143], v[118:119]
	v_cvt_pk_bf16_f32 v114, v112, v113
	v_pk_mul_f32 v[120:121], v[136:137], v[120:121]
	s_waitcnt lgkmcnt(0)
	v_add_f32_e32 v112, v115, v124
	v_mov_b32_e32 v113, v112
	s_nop 1
	v_permlane32_swap_b32_e32 v113, v112
	v_pk_mul_f32 v[116:117], v[138:139], v[122:123]
	v_cvt_pk_bf16_f32 v115, v118, v119
	v_cvt_pk_bf16_f32 v116, v116, v117
	v_cvt_pk_bf16_f32 v117, v120, v121
	global_store_dwordx4 v[194:195], v[114:117], off offset:256
	s_and_saveexec_b64 s[24:25], s[2:3]
	s_cbranch_execz .LBB0_1016
	v_lshl_add_u64 v[114:115], v[128:129], 2, s[14:15]
	s_waitcnt lgkmcnt(0)
	v_add_f32_e32 v112, v112, v113
	global_atomic_add_f32 v[114:115], v112, off
.LBB0_1016:
	s_or_b64 exec, exec, s[24:25]
	v_add_u32_e32 v112, s17, v179
	s_waitcnt lgkmcnt(0)
	v_ashrrev_i32_e32 v113, 31, v112
	v_lshlrev_b64 v[114:115], 12, v[112:113]
	v_lshl_add_u64 v[114:115], s[64:65], 0, v[114:115]
	v_lshl_add_u64 v[122:123], v[162:163], 2, v[114:115]
	global_load_dwordx4 v[114:117], v[122:123], off
	global_load_dwordx4 v[118:121], v[122:123], off offset:16
	global_load_dwordx4 v[232:235], v[122:123], off offset:512
	global_load_dwordx4 v[236:239], v[122:123], off offset:528
	v_lshlrev_b64 v[124:125], 11, v[112:113]
	v_lshl_add_u64 v[126:127], s[52:53], 0, v[124:125]
	v_lshl_add_u64 v[124:125], s[12:13], 0, v[124:125]
	v_lshl_add_u64 v[126:127], v[126:127], 0, v[164:165]
	v_lshl_add_u64 v[124:125], v[124:125], 0, v[164:165]
	s_waitcnt vmcnt(3)
	v_pk_fma_f32 v[116:117], v[110:111], v[90:91], v[116:117]
	v_pk_fma_f32 v[114:115], v[108:109], v[88:89], v[114:115]
	s_waitcnt vmcnt(2)
	v_pk_fma_f32 v[120:121], v[106:107], v[86:87], v[120:121]
	v_pk_fma_f32 v[118:119], v[104:105], v[84:85], v[118:119]
	v_cvt_pk_bf16_f32 v104, v114, v115
	v_cvt_pk_bf16_f32 v105, v116, v117
	v_cvt_pk_bf16_f32 v106, v118, v119
	v_cvt_pk_bf16_f32 v107, v120, v121
	v_pk_mul_f32 v[108:109], v[170:171], v[116:117]
	v_pk_mul_f32 v[110:111], v[174:175], v[114:115]
	v_pk_mul_f32 v[128:129], v[168:169], v[120:121]
	v_pk_mul_f32 v[130:131], v[172:173], v[118:119]
	global_store_dwordx4 v[126:127], v[104:107], off
	v_mul_f32_e32 v115, v115, v115
	v_mul_f32_e32 v117, v117, v117
	v_cvt_pk_bf16_f32 v104, v110, v111
	v_cvt_pk_bf16_f32 v105, v108, v109
	v_cvt_pk_bf16_f32 v106, v130, v131
	v_cvt_pk_bf16_f32 v107, v128, v129
	global_store_dwordx4 v[124:125], v[104:107], off
	s_waitcnt vmcnt(2)
	s_nop 1
	v_mov_b32_e32 v104, v232
	v_mov_b32_e32 v105, v233
	v_mov_b32_e32 v106, v234
	v_mov_b32_e32 v107, v235
	v_mov_b32_e32 v108, v236
	v_mov_b32_e32 v109, v237
	v_mov_b32_e32 v110, v238
	v_mov_b32_e32 v111, v239
	v_mul_f32_e32 v119, v119, v119
	v_fmac_f32_e32 v115, v114, v114
	v_fmac_f32_e32 v117, v116, v116
	v_mul_f32_e32 v121, v121, v121
	v_fmac_f32_e32 v119, v118, v118
	v_add_f32_e32 v114, v115, v117
	v_fmac_f32_e32 v121, v120, v120
	v_add_f32_e32 v114, v114, v119
	v_add_f32_e32 v114, v121, v114
	v_pk_fma_f32 v[102:103], v[102:103], v[94:95], v[106:107]
	v_pk_fma_f32 v[100:101], v[100:101], v[92:93], v[104:105]
	v_pk_fma_f32 v[104:105], v[98:99], v[82:83], v[110:111]
	v_pk_fma_f32 v[106:107], v[96:97], v[80:81], v[108:109]
	v_mul_f32_e32 v108, v101, v101
	v_mul_f32_e32 v109, v103, v103
	v_cvt_pk_bf16_f32 v96, v100, v101
	v_cvt_pk_bf16_f32 v97, v102, v103
	v_cvt_pk_bf16_f32 v98, v106, v107
	v_cvt_pk_bf16_f32 v99, v104, v105
	v_mul_f32_e32 v110, v107, v107
	v_fmac_f32_e32 v108, v100, v100
	v_fmac_f32_e32 v109, v102, v102
	v_mul_f32_e32 v111, v105, v105
	global_store_dwordx4 v[126:127], v[96:99], off offset:256
	v_fmac_f32_e32 v110, v106, v106
	v_fmac_f32_e32 v111, v104, v104
	v_add_f32_e32 v96, v108, v109
	v_add_f32_e32 v96, v96, v110
	v_add_f32_e32 v96, v111, v96
	v_add_f32_e32 v99, v114, v96
	v_mov_b32_e32 v108, v99
	s_nop 1
	v_permlane16_swap_b32_e32 v108, v99
	v_pk_mul_f32 v[96:97], v[140:141], v[100:101]
	v_pk_mul_f32 v[102:103], v[142:143], v[102:103]
	v_cvt_pk_bf16_f32 v98, v96, v97
	v_pk_mul_f32 v[104:105], v[136:137], v[104:105]
	s_waitcnt lgkmcnt(0)
	v_add_f32_e32 v96, v99, v108
	v_mov_b32_e32 v97, v96
	s_nop 1
	v_permlane32_swap_b32_e32 v97, v96
	v_pk_mul_f32 v[100:101], v[138:139], v[106:107]
	v_cvt_pk_bf16_f32 v99, v102, v103
	v_cvt_pk_bf16_f32 v100, v100, v101
	v_cvt_pk_bf16_f32 v101, v104, v105
	global_store_dwordx4 v[124:125], v[98:101], off offset:256
	s_and_saveexec_b64 s[24:25], s[2:3]
	s_cbranch_execz .LBB0_1018
	v_lshl_add_u64 v[98:99], v[112:113], 2, s[14:15]
	s_waitcnt lgkmcnt(0)
	v_add_f32_e32 v96, v96, v97
	global_atomic_add_f32 v[98:99], v96, off
.LBB0_1018:
	s_or_b64 exec, exec, s[24:25]
	v_add_u32_e32 v96, s17, v180
	s_waitcnt lgkmcnt(0)
	v_ashrrev_i32_e32 v97, 31, v96
	v_lshlrev_b64 v[98:99], 12, v[96:97]
	v_lshl_add_u64 v[98:99], s[64:65], 0, v[98:99]
	v_lshl_add_u64 v[106:107], v[162:163], 2, v[98:99]
	global_load_dwordx4 v[98:101], v[106:107], off
	global_load_dwordx4 v[102:105], v[106:107], off offset:16
	global_load_dwordx4 v[232:235], v[106:107], off offset:512
	global_load_dwordx4 v[236:239], v[106:107], off offset:528
	v_lshlrev_b64 v[108:109], 11, v[96:97]
	v_lshl_add_u64 v[110:111], s[52:53], 0, v[108:109]
	v_lshl_add_u64 v[108:109], s[12:13], 0, v[108:109]
	v_lshl_add_u64 v[110:111], v[110:111], 0, v[164:165]
	v_lshl_add_u64 v[108:109], v[108:109], 0, v[164:165]
	s_waitcnt vmcnt(3)
	v_pk_fma_f32 v[100:101], v[78:79], v[90:91], v[100:101]
	v_pk_fma_f32 v[98:99], v[76:77], v[88:89], v[98:99]
	s_waitcnt vmcnt(2)
	v_pk_fma_f32 v[104:105], v[74:75], v[86:87], v[104:105]
	v_pk_fma_f32 v[102:103], v[72:73], v[84:85], v[102:103]
	v_cvt_pk_bf16_f32 v72, v98, v99
	v_cvt_pk_bf16_f32 v73, v100, v101
	v_cvt_pk_bf16_f32 v74, v102, v103
	v_cvt_pk_bf16_f32 v75, v104, v105
	v_pk_mul_f32 v[76:77], v[170:171], v[100:101]
	v_pk_mul_f32 v[78:79], v[174:175], v[98:99]
	v_pk_mul_f32 v[112:113], v[168:169], v[104:105]
	v_pk_mul_f32 v[114:115], v[172:173], v[102:103]
	global_store_dwordx4 v[110:111], v[72:75], off
	v_mul_f32_e32 v99, v99, v99
	v_mul_f32_e32 v101, v101, v101
	v_cvt_pk_bf16_f32 v72, v78, v79
	v_cvt_pk_bf16_f32 v73, v76, v77
	v_cvt_pk_bf16_f32 v74, v114, v115
	v_cvt_pk_bf16_f32 v75, v112, v113
	global_store_dwordx4 v[108:109], v[72:75], off
	s_waitcnt vmcnt(2)
	s_nop 1
	v_mov_b32_e32 v72, v232
	v_mov_b32_e32 v73, v233
	v_mov_b32_e32 v74, v234
	v_mov_b32_e32 v75, v235
	v_mov_b32_e32 v76, v236
	v_mov_b32_e32 v77, v237
	v_mov_b32_e32 v78, v238
	v_mov_b32_e32 v79, v239
	v_mul_f32_e32 v103, v103, v103
	v_fmac_f32_e32 v99, v98, v98
	v_fmac_f32_e32 v101, v100, v100
	v_mul_f32_e32 v105, v105, v105
	v_fmac_f32_e32 v103, v102, v102
	v_add_f32_e32 v98, v99, v101
	v_fmac_f32_e32 v105, v104, v104
	v_add_f32_e32 v98, v98, v103
	v_add_f32_e32 v98, v105, v98
	v_pk_fma_f32 v[70:71], v[70:71], v[94:95], v[74:75]
	v_pk_fma_f32 v[68:69], v[68:69], v[92:93], v[72:73]
	v_pk_fma_f32 v[72:73], v[66:67], v[82:83], v[78:79]
	v_pk_fma_f32 v[74:75], v[64:65], v[80:81], v[76:77]
	v_mul_f32_e32 v76, v69, v69
	v_mul_f32_e32 v77, v71, v71
	v_cvt_pk_bf16_f32 v64, v68, v69
	v_cvt_pk_bf16_f32 v65, v70, v71
	v_cvt_pk_bf16_f32 v66, v74, v75
	v_cvt_pk_bf16_f32 v67, v72, v73
	v_mul_f32_e32 v78, v75, v75
	v_fmac_f32_e32 v76, v68, v68
	v_fmac_f32_e32 v77, v70, v70
	v_mul_f32_e32 v79, v73, v73
	global_store_dwordx4 v[110:111], v[64:67], off offset:256
	v_fmac_f32_e32 v78, v74, v74
	v_fmac_f32_e32 v79, v72, v72
	v_add_f32_e32 v64, v76, v77
	v_add_f32_e32 v64, v64, v78
	v_add_f32_e32 v64, v79, v64
	v_add_f32_e32 v67, v98, v64
	v_mov_b32_e32 v76, v67
	s_nop 1
	v_permlane16_swap_b32_e32 v76, v67
	v_pk_mul_f32 v[64:65], v[140:141], v[68:69]
	v_pk_mul_f32 v[70:71], v[142:143], v[70:71]
	v_cvt_pk_bf16_f32 v66, v64, v65
	v_pk_mul_f32 v[72:73], v[136:137], v[72:73]
	s_waitcnt lgkmcnt(0)
	v_add_f32_e32 v64, v67, v76
	v_mov_b32_e32 v65, v64
	s_nop 1
	v_permlane32_swap_b32_e32 v65, v64
	v_pk_mul_f32 v[68:69], v[138:139], v[74:75]
	v_cvt_pk_bf16_f32 v67, v70, v71
	v_cvt_pk_bf16_f32 v68, v68, v69
	v_cvt_pk_bf16_f32 v69, v72, v73
	global_store_dwordx4 v[108:109], v[66:69], off offset:256
	s_and_saveexec_b64 s[24:25], s[2:3]
	s_cbranch_execz .LBB0_1020
	v_lshl_add_u64 v[66:67], v[96:97], 2, s[14:15]
	s_waitcnt lgkmcnt(0)
	v_add_f32_e32 v64, v64, v65
	global_atomic_add_f32 v[66:67], v64, off
.LBB0_1020:
	s_or_b64 exec, exec, s[24:25]
	v_add_u32_e32 v64, 0x80, v166
	s_waitcnt lgkmcnt(0)
	v_ashrrev_i32_e32 v65, 31, v64
	v_lshlrev_b64 v[66:67], 12, v[64:65]
	v_lshl_add_u64 v[66:67], s[64:65], 0, v[66:67]
	v_lshl_add_u64 v[74:75], v[162:163], 2, v[66:67]
	global_load_dwordx4 v[66:69], v[74:75], off
	global_load_dwordx4 v[70:73], v[74:75], off offset:16
	global_load_dwordx4 v[232:235], v[74:75], off offset:512
	global_load_dwordx4 v[236:239], v[74:75], off offset:528
	v_lshlrev_b64 v[76:77], 11, v[64:65]
	v_lshl_add_u64 v[78:79], s[52:53], 0, v[76:77]
	v_lshl_add_u64 v[76:77], s[12:13], 0, v[76:77]
	v_lshl_add_u64 v[78:79], v[78:79], 0, v[164:165]
	v_lshl_add_u64 v[76:77], v[76:77], 0, v[164:165]
	s_waitcnt vmcnt(3)
	v_pk_fma_f32 v[68:69], v[62:63], v[90:91], v[68:69]
	v_pk_fma_f32 v[66:67], v[60:61], v[88:89], v[66:67]
	s_waitcnt vmcnt(2)
	v_pk_fma_f32 v[72:73], v[58:59], v[86:87], v[72:73]
	v_pk_fma_f32 v[70:71], v[56:57], v[84:85], v[70:71]
	v_cvt_pk_bf16_f32 v56, v66, v67
	v_cvt_pk_bf16_f32 v57, v68, v69
	v_cvt_pk_bf16_f32 v58, v70, v71
	v_cvt_pk_bf16_f32 v59, v72, v73
	v_pk_mul_f32 v[60:61], v[170:171], v[68:69]
	v_pk_mul_f32 v[62:63], v[174:175], v[66:67]
	v_pk_mul_f32 v[96:97], v[168:169], v[72:73]
	v_pk_mul_f32 v[98:99], v[172:173], v[70:71]
	global_store_dwordx4 v[78:79], v[56:59], off
	v_mul_f32_e32 v67, v67, v67
	v_mul_f32_e32 v69, v69, v69
	v_cvt_pk_bf16_f32 v56, v62, v63
	v_cvt_pk_bf16_f32 v57, v60, v61
	v_cvt_pk_bf16_f32 v58, v98, v99
	v_cvt_pk_bf16_f32 v59, v96, v97
	global_store_dwordx4 v[76:77], v[56:59], off
	s_waitcnt vmcnt(2)
	s_nop 1
	v_mov_b32_e32 v56, v232
	v_mov_b32_e32 v57, v233
	v_mov_b32_e32 v58, v234
	v_mov_b32_e32 v59, v235
	v_mov_b32_e32 v60, v236
	v_mov_b32_e32 v61, v237
	v_mov_b32_e32 v62, v238
	v_mov_b32_e32 v63, v239
	v_mul_f32_e32 v71, v71, v71
	v_fmac_f32_e32 v67, v66, v66
	v_fmac_f32_e32 v69, v68, v68
	v_mul_f32_e32 v73, v73, v73
	v_fmac_f32_e32 v71, v70, v70
	v_add_f32_e32 v66, v67, v69
	v_fmac_f32_e32 v73, v72, v72
	v_add_f32_e32 v66, v66, v71
	v_add_f32_e32 v66, v73, v66
	v_pk_fma_f32 v[54:55], v[54:55], v[94:95], v[58:59]
	v_pk_fma_f32 v[52:53], v[52:53], v[92:93], v[56:57]
	v_pk_fma_f32 v[56:57], v[50:51], v[82:83], v[62:63]
	v_pk_fma_f32 v[58:59], v[48:49], v[80:81], v[60:61]
	v_mul_f32_e32 v60, v53, v53
	v_mul_f32_e32 v61, v55, v55
	v_cvt_pk_bf16_f32 v48, v52, v53
	v_cvt_pk_bf16_f32 v49, v54, v55
	v_cvt_pk_bf16_f32 v50, v58, v59
	v_cvt_pk_bf16_f32 v51, v56, v57
	v_mul_f32_e32 v62, v59, v59
	v_fmac_f32_e32 v60, v52, v52
	v_fmac_f32_e32 v61, v54, v54
	v_mul_f32_e32 v63, v57, v57
	global_store_dwordx4 v[78:79], v[48:51], off offset:256
	v_fmac_f32_e32 v62, v58, v58
	v_fmac_f32_e32 v63, v56, v56
	v_add_f32_e32 v48, v60, v61
	v_add_f32_e32 v48, v48, v62
	v_add_f32_e32 v48, v63, v48
	v_add_f32_e32 v51, v66, v48
	v_mov_b32_e32 v60, v51
	s_nop 1
	v_permlane16_swap_b32_e32 v60, v51
	v_pk_mul_f32 v[48:49], v[140:141], v[52:53]
	v_pk_mul_f32 v[54:55], v[142:143], v[54:55]
	v_cvt_pk_bf16_f32 v50, v48, v49
	v_pk_mul_f32 v[56:57], v[136:137], v[56:57]
	s_waitcnt lgkmcnt(0)
	v_add_f32_e32 v48, v51, v60
	v_mov_b32_e32 v49, v48
	s_nop 1
	v_permlane32_swap_b32_e32 v49, v48
	v_pk_mul_f32 v[52:53], v[138:139], v[58:59]
	v_cvt_pk_bf16_f32 v51, v54, v55
	v_cvt_pk_bf16_f32 v52, v52, v53
	v_cvt_pk_bf16_f32 v53, v56, v57
	global_store_dwordx4 v[76:77], v[50:53], off offset:256
	s_and_saveexec_b64 s[24:25], s[2:3]
	s_cbranch_execz .LBB0_1022
	v_lshl_add_u64 v[50:51], v[64:65], 2, s[14:15]
	s_waitcnt lgkmcnt(0)
	v_add_f32_e32 v48, v48, v49
	global_atomic_add_f32 v[50:51], v48, off
.LBB0_1022:
	s_or_b64 exec, exec, s[24:25]
	v_add_u32_e32 v48, 0x90, v166
	s_waitcnt lgkmcnt(0)
	v_ashrrev_i32_e32 v49, 31, v48
	v_lshlrev_b64 v[50:51], 12, v[48:49]
	v_lshl_add_u64 v[50:51], s[64:65], 0, v[50:51]
	v_lshl_add_u64 v[58:59], v[162:163], 2, v[50:51]
	global_load_dwordx4 v[50:53], v[58:59], off
	global_load_dwordx4 v[54:57], v[58:59], off offset:16
	global_load_dwordx4 v[232:235], v[58:59], off offset:512
	global_load_dwordx4 v[236:239], v[58:59], off offset:528
	v_lshlrev_b64 v[60:61], 11, v[48:49]
	v_lshl_add_u64 v[62:63], s[52:53], 0, v[60:61]
	v_lshl_add_u64 v[60:61], s[12:13], 0, v[60:61]
	v_lshl_add_u64 v[62:63], v[62:63], 0, v[164:165]
	v_lshl_add_u64 v[60:61], v[60:61], 0, v[164:165]
	s_waitcnt vmcnt(3)
	v_pk_fma_f32 v[52:53], v[46:47], v[90:91], v[52:53]
	v_pk_fma_f32 v[50:51], v[44:45], v[88:89], v[50:51]
	s_waitcnt vmcnt(2)
	v_pk_fma_f32 v[56:57], v[42:43], v[86:87], v[56:57]
	v_pk_fma_f32 v[54:55], v[40:41], v[84:85], v[54:55]
	v_cvt_pk_bf16_f32 v40, v50, v51
	v_cvt_pk_bf16_f32 v41, v52, v53
	v_cvt_pk_bf16_f32 v42, v54, v55
	v_cvt_pk_bf16_f32 v43, v56, v57
	v_pk_mul_f32 v[44:45], v[170:171], v[52:53]
	v_pk_mul_f32 v[46:47], v[174:175], v[50:51]
	v_pk_mul_f32 v[64:65], v[168:169], v[56:57]
	v_pk_mul_f32 v[66:67], v[172:173], v[54:55]
	global_store_dwordx4 v[62:63], v[40:43], off
	v_mul_f32_e32 v51, v51, v51
	v_mul_f32_e32 v53, v53, v53
	v_cvt_pk_bf16_f32 v40, v46, v47
	v_cvt_pk_bf16_f32 v41, v44, v45
	v_cvt_pk_bf16_f32 v42, v66, v67
	v_cvt_pk_bf16_f32 v43, v64, v65
	global_store_dwordx4 v[60:61], v[40:43], off
	s_waitcnt vmcnt(2)
	s_nop 1
	v_mov_b32_e32 v40, v232
	v_mov_b32_e32 v41, v233
	v_mov_b32_e32 v42, v234
	v_mov_b32_e32 v43, v235
	v_mov_b32_e32 v44, v236
	v_mov_b32_e32 v45, v237
	v_mov_b32_e32 v46, v238
	v_mov_b32_e32 v47, v239
	v_mul_f32_e32 v55, v55, v55
	v_fmac_f32_e32 v51, v50, v50
	v_fmac_f32_e32 v53, v52, v52
	v_mul_f32_e32 v57, v57, v57
	v_fmac_f32_e32 v55, v54, v54
	v_add_f32_e32 v50, v51, v53
	v_fmac_f32_e32 v57, v56, v56
	v_add_f32_e32 v50, v50, v55
	v_add_f32_e32 v50, v57, v50
	v_pk_fma_f32 v[38:39], v[38:39], v[94:95], v[42:43]
	v_pk_fma_f32 v[36:37], v[36:37], v[92:93], v[40:41]
	v_pk_fma_f32 v[40:41], v[34:35], v[82:83], v[46:47]
	v_pk_fma_f32 v[42:43], v[32:33], v[80:81], v[44:45]
	v_mul_f32_e32 v44, v37, v37
	v_mul_f32_e32 v45, v39, v39
	v_cvt_pk_bf16_f32 v32, v36, v37
	v_cvt_pk_bf16_f32 v33, v38, v39
	v_cvt_pk_bf16_f32 v34, v42, v43
	v_cvt_pk_bf16_f32 v35, v40, v41
	v_mul_f32_e32 v46, v43, v43
	v_fmac_f32_e32 v44, v36, v36
	v_fmac_f32_e32 v45, v38, v38
	v_mul_f32_e32 v47, v41, v41
	global_store_dwordx4 v[62:63], v[32:35], off offset:256
	v_fmac_f32_e32 v46, v42, v42
	v_fmac_f32_e32 v47, v40, v40
	v_add_f32_e32 v32, v44, v45
	v_add_f32_e32 v32, v32, v46
	v_add_f32_e32 v32, v47, v32
	v_add_f32_e32 v35, v50, v32
	v_mov_b32_e32 v44, v35
	s_nop 1
	v_permlane16_swap_b32_e32 v44, v35
	v_pk_mul_f32 v[32:33], v[140:141], v[36:37]
	v_pk_mul_f32 v[38:39], v[142:143], v[38:39]
	v_cvt_pk_bf16_f32 v34, v32, v33
	v_pk_mul_f32 v[40:41], v[136:137], v[40:41]
	s_waitcnt lgkmcnt(0)
	v_add_f32_e32 v32, v35, v44
	v_mov_b32_e32 v33, v32
	s_nop 1
	v_permlane32_swap_b32_e32 v33, v32
	v_pk_mul_f32 v[36:37], v[138:139], v[42:43]
	v_cvt_pk_bf16_f32 v35, v38, v39
	v_cvt_pk_bf16_f32 v36, v36, v37
	v_cvt_pk_bf16_f32 v37, v40, v41
	global_store_dwordx4 v[60:61], v[34:37], off offset:256
	s_and_saveexec_b64 s[24:25], s[2:3]
	s_cbranch_execz .LBB0_1024
	v_lshl_add_u64 v[34:35], v[48:49], 2, s[14:15]
	s_waitcnt lgkmcnt(0)
	v_add_f32_e32 v32, v32, v33
	global_atomic_add_f32 v[34:35], v32, off
.LBB0_1024:
	s_or_b64 exec, exec, s[24:25]
	v_add_u32_e32 v32, 0xa0, v166
	s_waitcnt lgkmcnt(0)
	v_ashrrev_i32_e32 v33, 31, v32
	v_lshlrev_b64 v[34:35], 12, v[32:33]
	v_lshl_add_u64 v[34:35], s[64:65], 0, v[34:35]
	v_lshl_add_u64 v[42:43], v[162:163], 2, v[34:35]
	global_load_dwordx4 v[34:37], v[42:43], off
	global_load_dwordx4 v[38:41], v[42:43], off offset:16
	global_load_dwordx4 v[232:235], v[42:43], off offset:512
	global_load_dwordx4 v[236:239], v[42:43], off offset:528
	v_lshlrev_b64 v[44:45], 11, v[32:33]
	v_lshl_add_u64 v[46:47], s[52:53], 0, v[44:45]
	v_lshl_add_u64 v[44:45], s[12:13], 0, v[44:45]
	v_lshl_add_u64 v[46:47], v[46:47], 0, v[164:165]
	v_lshl_add_u64 v[44:45], v[44:45], 0, v[164:165]
	s_waitcnt vmcnt(3)
	v_pk_fma_f32 v[36:37], v[30:31], v[90:91], v[36:37]
	v_pk_fma_f32 v[34:35], v[28:29], v[88:89], v[34:35]
	s_waitcnt vmcnt(2)
	v_pk_fma_f32 v[40:41], v[26:27], v[86:87], v[40:41]
	v_pk_fma_f32 v[38:39], v[24:25], v[84:85], v[38:39]
	v_cvt_pk_bf16_f32 v24, v34, v35
	v_cvt_pk_bf16_f32 v25, v36, v37
	v_cvt_pk_bf16_f32 v26, v38, v39
	v_cvt_pk_bf16_f32 v27, v40, v41
	v_pk_mul_f32 v[28:29], v[170:171], v[36:37]
	v_pk_mul_f32 v[30:31], v[174:175], v[34:35]
	v_pk_mul_f32 v[48:49], v[168:169], v[40:41]
	v_pk_mul_f32 v[50:51], v[172:173], v[38:39]
	global_store_dwordx4 v[46:47], v[24:27], off
	v_mul_f32_e32 v35, v35, v35
	v_mul_f32_e32 v37, v37, v37
	v_cvt_pk_bf16_f32 v24, v30, v31
	v_cvt_pk_bf16_f32 v25, v28, v29
	v_cvt_pk_bf16_f32 v26, v50, v51
	v_cvt_pk_bf16_f32 v27, v48, v49
	global_store_dwordx4 v[44:45], v[24:27], off
	s_waitcnt vmcnt(2)
	s_nop 1
	v_mov_b32_e32 v24, v232
	v_mov_b32_e32 v25, v233
	v_mov_b32_e32 v26, v234
	v_mov_b32_e32 v27, v235
	v_mov_b32_e32 v28, v236
	v_mov_b32_e32 v29, v237
	v_mov_b32_e32 v30, v238
	v_mov_b32_e32 v31, v239
	v_mul_f32_e32 v39, v39, v39
	v_fmac_f32_e32 v35, v34, v34
	v_fmac_f32_e32 v37, v36, v36
	v_mul_f32_e32 v41, v41, v41
	v_fmac_f32_e32 v39, v38, v38
	v_add_f32_e32 v34, v35, v37
	v_fmac_f32_e32 v41, v40, v40
	v_add_f32_e32 v34, v34, v39
	v_add_f32_e32 v34, v41, v34
	v_pk_fma_f32 v[22:23], v[22:23], v[94:95], v[26:27]
	v_pk_fma_f32 v[20:21], v[20:21], v[92:93], v[24:25]
	v_pk_fma_f32 v[24:25], v[18:19], v[82:83], v[30:31]
	v_pk_fma_f32 v[26:27], v[16:17], v[80:81], v[28:29]
	v_mul_f32_e32 v28, v21, v21
	v_mul_f32_e32 v29, v23, v23
	v_cvt_pk_bf16_f32 v16, v20, v21
	v_cvt_pk_bf16_f32 v17, v22, v23
	v_cvt_pk_bf16_f32 v18, v26, v27
	v_cvt_pk_bf16_f32 v19, v24, v25
	v_mul_f32_e32 v30, v27, v27
	v_fmac_f32_e32 v28, v20, v20
	v_fmac_f32_e32 v29, v22, v22
	v_mul_f32_e32 v31, v25, v25
	global_store_dwordx4 v[46:47], v[16:19], off offset:256
	v_fmac_f32_e32 v30, v26, v26
	v_fmac_f32_e32 v31, v24, v24
	v_add_f32_e32 v16, v28, v29
	v_add_f32_e32 v16, v16, v30
	v_add_f32_e32 v16, v31, v16
	v_add_f32_e32 v19, v34, v16
	v_mov_b32_e32 v28, v19
	s_nop 1
	v_permlane16_swap_b32_e32 v28, v19
	v_pk_mul_f32 v[16:17], v[140:141], v[20:21]
	v_pk_mul_f32 v[22:23], v[142:143], v[22:23]
	v_cvt_pk_bf16_f32 v18, v16, v17
	v_pk_mul_f32 v[24:25], v[136:137], v[24:25]
	s_waitcnt lgkmcnt(0)
	v_add_f32_e32 v16, v19, v28
	v_mov_b32_e32 v17, v16
	s_nop 1
	v_permlane32_swap_b32_e32 v17, v16
	v_pk_mul_f32 v[20:21], v[138:139], v[26:27]
	v_cvt_pk_bf16_f32 v19, v22, v23
	v_cvt_pk_bf16_f32 v20, v20, v21
	v_cvt_pk_bf16_f32 v21, v24, v25
	global_store_dwordx4 v[44:45], v[18:21], off offset:256
	s_and_saveexec_b64 s[24:25], s[2:3]
	s_cbranch_execz .LBB0_1026
	v_lshl_add_u64 v[18:19], v[32:33], 2, s[14:15]
	s_waitcnt lgkmcnt(0)
	v_add_f32_e32 v16, v16, v17
	global_atomic_add_f32 v[18:19], v16, off
.LBB0_1026:
	s_or_b64 exec, exec, s[24:25]
	v_add_u32_e32 v16, 0xb0, v166
	s_waitcnt lgkmcnt(0)
	v_ashrrev_i32_e32 v17, 31, v16
	v_lshlrev_b64 v[18:19], 12, v[16:17]
	v_lshl_add_u64 v[18:19], s[64:65], 0, v[18:19]
	v_lshl_add_u64 v[26:27], v[162:163], 2, v[18:19]
	global_load_dwordx4 v[18:21], v[26:27], off
	global_load_dwordx4 v[22:25], v[26:27], off offset:16
	global_load_dwordx4 v[232:235], v[26:27], off offset:512
	global_load_dwordx4 v[236:239], v[26:27], off offset:528
	v_lshlrev_b64 v[28:29], 11, v[16:17]
	v_lshl_add_u64 v[30:31], s[52:53], 0, v[28:29]
	v_lshl_add_u64 v[28:29], s[12:13], 0, v[28:29]
	v_lshl_add_u64 v[30:31], v[30:31], 0, v[164:165]
	v_lshl_add_u64 v[28:29], v[28:29], 0, v[164:165]
	s_waitcnt vmcnt(3)
	v_pk_fma_f32 v[20:21], v[14:15], v[90:91], v[20:21]
	v_pk_fma_f32 v[18:19], v[12:13], v[88:89], v[18:19]
	s_waitcnt vmcnt(2)
	v_pk_fma_f32 v[24:25], v[10:11], v[86:87], v[24:25]
	v_pk_fma_f32 v[22:23], v[8:9], v[84:85], v[22:23]
	v_cvt_pk_bf16_f32 v8, v18, v19
	v_cvt_pk_bf16_f32 v9, v20, v21
	v_cvt_pk_bf16_f32 v10, v22, v23
	v_cvt_pk_bf16_f32 v11, v24, v25
	v_pk_mul_f32 v[12:13], v[170:171], v[20:21]
	v_pk_mul_f32 v[14:15], v[174:175], v[18:19]
	v_pk_mul_f32 v[32:33], v[168:169], v[24:25]
	v_pk_mul_f32 v[34:35], v[172:173], v[22:23]
	global_store_dwordx4 v[30:31], v[8:11], off
	v_mul_f32_e32 v19, v19, v19
	v_mul_f32_e32 v21, v21, v21
	v_cvt_pk_bf16_f32 v8, v14, v15
	v_cvt_pk_bf16_f32 v9, v12, v13
	v_cvt_pk_bf16_f32 v10, v34, v35
	v_cvt_pk_bf16_f32 v11, v32, v33
	global_store_dwordx4 v[28:29], v[8:11], off
	s_waitcnt vmcnt(2)
	s_nop 1
	v_mov_b32_e32 v8, v232
	v_mov_b32_e32 v9, v233
	v_mov_b32_e32 v10, v234
	v_mov_b32_e32 v11, v235
	v_mov_b32_e32 v12, v236
	v_mov_b32_e32 v13, v237
	v_mov_b32_e32 v14, v238
	v_mov_b32_e32 v15, v239
	v_mul_f32_e32 v23, v23, v23
	v_fmac_f32_e32 v19, v18, v18
	v_fmac_f32_e32 v21, v20, v20
	v_mul_f32_e32 v25, v25, v25
	v_fmac_f32_e32 v23, v22, v22
	v_add_f32_e32 v18, v19, v21
	v_fmac_f32_e32 v25, v24, v24
	v_add_f32_e32 v18, v18, v23
	v_add_f32_e32 v18, v25, v18
	v_pk_fma_f32 v[6:7], v[6:7], v[94:95], v[10:11]
	v_pk_fma_f32 v[4:5], v[4:5], v[92:93], v[8:9]
	v_pk_fma_f32 v[8:9], v[2:3], v[82:83], v[14:15]
	v_pk_fma_f32 v[10:11], v[0:1], v[80:81], v[12:13]
	v_mul_f32_e32 v12, v5, v5
	v_mul_f32_e32 v13, v7, v7
	v_cvt_pk_bf16_f32 v0, v4, v5
	v_cvt_pk_bf16_f32 v1, v6, v7
	v_cvt_pk_bf16_f32 v2, v10, v11
	v_cvt_pk_bf16_f32 v3, v8, v9
	v_mul_f32_e32 v14, v11, v11
	v_fmac_f32_e32 v12, v4, v4
	v_fmac_f32_e32 v13, v6, v6
	v_mul_f32_e32 v15, v9, v9
	global_store_dwordx4 v[30:31], v[0:3], off offset:256
	v_fmac_f32_e32 v14, v10, v10
	v_fmac_f32_e32 v15, v8, v8
	v_add_f32_e32 v0, v12, v13
	v_add_f32_e32 v0, v0, v14
	v_add_f32_e32 v0, v15, v0
	v_add_f32_e32 v3, v18, v0
	v_mov_b32_e32 v12, v3
	s_nop 1
	v_permlane16_swap_b32_e32 v12, v3
	v_pk_mul_f32 v[0:1], v[140:141], v[4:5]
	v_pk_mul_f32 v[6:7], v[142:143], v[6:7]
	v_cvt_pk_bf16_f32 v2, v0, v1
	v_pk_mul_f32 v[8:9], v[136:137], v[8:9]
	s_waitcnt lgkmcnt(0)
	v_add_f32_e32 v0, v3, v12
	v_mov_b32_e32 v1, v0
	s_nop 1
	v_permlane32_swap_b32_e32 v1, v0
	v_pk_mul_f32 v[4:5], v[138:139], v[10:11]
	v_cvt_pk_bf16_f32 v3, v6, v7
	v_cvt_pk_bf16_f32 v4, v4, v5
	v_cvt_pk_bf16_f32 v5, v8, v9
	global_store_dwordx4 v[28:29], v[2:5], off offset:256
	s_and_saveexec_b64 s[24:25], s[2:3]
	s_cbranch_execz .LBB0_1028
	v_lshl_add_u64 v[2:3], v[16:17], 2, s[14:15]
	s_waitcnt lgkmcnt(0)
	v_add_f32_e32 v0, v0, v1
	global_atomic_add_f32 v[2:3], v0, off
